# adds hand-written steady-state loop for forgetting-attention units (bias row via MFMA C operand, in-place accumulators, conditional rescale)
# speedup vs baseline: 1.0201x; 1.0184x over previous
.LBB0_437:
	s_and_b64 vcc, exec, s[16:17]
	s_cbranch_vccz .LBB0_439
	s_waitcnt vmcnt(0)
	s_mov_b32 s98, 0x3e38aa3b
	ds_read2_b32 v[114:115], v0 offset1:1
	ds_read2_b32 v[116:117], v0 offset0:2 offset1:3
	ds_read2_b32 v[118:119], v0 offset0:8 offset1:9
	ds_read2_b32 v[120:121], v0 offset0:10 offset1:11
	ds_read2_b32 v[122:123], v0 offset0:16 offset1:17
	ds_read2_b32 v[124:125], v0 offset0:18 offset1:19
	ds_read2_b32 v[126:127], v0 offset0:24 offset1:25
	ds_read2_b32 v[128:129], v0 offset0:26 offset1:27
.Lfx_iter:
	s_waitcnt lgkmcnt(0)
	v_mul_f32_e32 v114, 0x40b17218, v114
	v_mul_f32_e32 v115, 0x40b17218, v115
	v_mul_f32_e32 v116, 0x40b17218, v116
	v_mul_f32_e32 v117, 0x40b17218, v117
	v_mul_f32_e32 v118, 0x40b17218, v118
	v_mul_f32_e32 v119, 0x40b17218, v119
	v_mul_f32_e32 v120, 0x40b17218, v120
	v_mul_f32_e32 v121, 0x40b17218, v121
	v_mul_f32_e32 v122, 0x40b17218, v122
	v_mul_f32_e32 v123, 0x40b17218, v123
	v_mul_f32_e32 v124, 0x40b17218, v124
	v_mul_f32_e32 v125, 0x40b17218, v125
	v_mul_f32_e32 v126, 0x40b17218, v126
	v_mul_f32_e32 v127, 0x40b17218, v127
	v_mul_f32_e32 v128, 0x40b17218, v128
	v_mul_f32_e32 v129, 0x40b17218, v129
	s_nop 1
	v_mfma_f32_32x32x16_bf16 v[2:17], v[206:209], v[130:133], v[114:129]
	v_mfma_f32_32x32x16_bf16 v[18:33], v[206:209], v[146:149], v[114:129]
	v_mfma_f32_32x32x16_bf16 v[2:17], v[202:205], v[134:137], v[2:17]
	v_mfma_f32_32x32x16_bf16 v[18:33], v[202:205], v[150:153], v[18:33]
	v_mfma_f32_32x32x16_bf16 v[2:17], v[198:201], v[138:141], v[2:17]
	v_mfma_f32_32x32x16_bf16 v[18:33], v[198:201], v[154:157], v[18:33]
	v_mfma_f32_32x32x16_bf16 v[2:17], v[194:197], v[142:145], v[2:17]
	v_mfma_f32_32x32x16_bf16 v[18:33], v[194:197], v[158:161], v[18:33]
	s_nop 10
	v_max3_f32 v230, v2, v3, v4
	v_max3_f32 v231, v5, v6, v7
	v_max3_f32 v232, v8, v9, v10
	v_max3_f32 v233, v11, v12, v13
	v_max3_f32 v230, v230, v14, v15
	v_max3_f32 v231, v231, v16, v17
	v_max3_f32 v230, v230, v231, v232
	v_max_f32_e32 v230, v230, v233
	v_mul_f32_e32 v230, s98, v230
	v_mov_b32_e32 v231, v230
	s_nop 1
	v_permlane32_swap_b32_e32 v230, v231
	v_max3_f32 v220, v224, v230, v231
	v_sub_f32_e32 v232, v224, v220
	v_exp_f32_e32 v226, v232
	v_fma_f32 v2, v2, s98, -v220
	v_fma_f32 v3, v3, s98, -v220
	v_fma_f32 v4, v4, s98, -v220
	v_fma_f32 v5, v5, s98, -v220
	v_fma_f32 v6, v6, s98, -v220
	v_fma_f32 v7, v7, s98, -v220
	v_fma_f32 v8, v8, s98, -v220
	v_fma_f32 v9, v9, s98, -v220
	v_fma_f32 v10, v10, s98, -v220
	v_fma_f32 v11, v11, s98, -v220
	v_fma_f32 v12, v12, s98, -v220
	v_fma_f32 v13, v13, s98, -v220
	v_fma_f32 v14, v14, s98, -v220
	v_fma_f32 v15, v15, s98, -v220
	v_fma_f32 v16, v16, s98, -v220
	v_fma_f32 v17, v17, s98, -v220
	v_exp_f32_e32 v2, v2
	v_exp_f32_e32 v3, v3
	v_exp_f32_e32 v4, v4
	v_exp_f32_e32 v5, v5
	v_exp_f32_e32 v6, v6
	v_exp_f32_e32 v7, v7
	v_exp_f32_e32 v8, v8
	v_exp_f32_e32 v9, v9
	v_exp_f32_e32 v10, v10
	v_exp_f32_e32 v11, v11
	v_exp_f32_e32 v12, v12
	v_exp_f32_e32 v13, v13
	v_exp_f32_e32 v14, v14
	v_exp_f32_e32 v15, v15
	v_exp_f32_e32 v16, v16
	v_exp_f32_e32 v17, v17
	v_cmp_lt_f32_e32 vcc, v224, v220
	v_mov_b32_e32 v224, v220
	v_cvt_pk_bf16_f32 v98, v2, v3
	v_cvt_pk_bf16_f32 v99, v4, v5
	v_cvt_pk_bf16_f32 v100, v6, v7
	v_cvt_pk_bf16_f32 v101, v8, v9
	v_cvt_pk_bf16_f32 v102, v10, v11
	v_cvt_pk_bf16_f32 v103, v12, v13
	v_cvt_pk_bf16_f32 v104, v14, v15
	v_cvt_pk_bf16_f32 v105, v16, v17
	v_add_f32_e32 v230, v2, v3
	v_add_f32_e32 v231, v4, v5
	v_add_f32_e32 v232, v6, v7
	v_add_f32_e32 v233, v8, v9
	v_add_f32_e32 v230, v230, v10
	v_add_f32_e32 v231, v231, v11
	v_add_f32_e32 v232, v232, v12
	v_add_f32_e32 v233, v233, v13
	v_add_f32_e32 v230, v230, v14
	v_add_f32_e32 v231, v231, v15
	v_add_f32_e32 v232, v232, v16
	v_add_f32_e32 v233, v233, v17
	v_add_f32_e32 v230, v230, v231
	v_add_f32_e32 v232, v232, v233
	v_add_f32_e32 v230, v230, v232
	v_fmac_f32_e32 v230, v218, v226
	v_mov_b32_e32 v218, v230
	s_cbranch_vccz .Lfx_nr0
	v_pk_mul_f32 v[82:83], v[82:83], v[226:227] op_sel_hi:[1,0]
	v_pk_mul_f32 v[84:85], v[84:85], v[226:227] op_sel_hi:[1,0]
	v_pk_mul_f32 v[86:87], v[86:87], v[226:227] op_sel_hi:[1,0]
	v_pk_mul_f32 v[88:89], v[88:89], v[226:227] op_sel_hi:[1,0]
	v_pk_mul_f32 v[90:91], v[90:91], v[226:227] op_sel_hi:[1,0]
	v_pk_mul_f32 v[92:93], v[92:93], v[226:227] op_sel_hi:[1,0]
	v_pk_mul_f32 v[94:95], v[94:95], v[226:227] op_sel_hi:[1,0]
	v_pk_mul_f32 v[96:97], v[96:97], v[226:227] op_sel_hi:[1,0]
	v_pk_mul_f32 v[66:67], v[66:67], v[226:227] op_sel_hi:[1,0]
	v_pk_mul_f32 v[68:69], v[68:69], v[226:227] op_sel_hi:[1,0]
	v_pk_mul_f32 v[70:71], v[70:71], v[226:227] op_sel_hi:[1,0]
	v_pk_mul_f32 v[72:73], v[72:73], v[226:227] op_sel_hi:[1,0]
	v_pk_mul_f32 v[74:75], v[74:75], v[226:227] op_sel_hi:[1,0]
	v_pk_mul_f32 v[76:77], v[76:77], v[226:227] op_sel_hi:[1,0]
	v_pk_mul_f32 v[78:79], v[78:79], v[226:227] op_sel_hi:[1,0]
	v_pk_mul_f32 v[80:81], v[80:81], v[226:227] op_sel_hi:[1,0]
	s_nop 1
.Lfx_nr0:
	s_waitcnt vmcnt(4)
	v_mfma_f32_32x32x16_bf16 v[82:97], v[190:193], v[98:101], v[82:97]
	v_mfma_f32_32x32x16_bf16 v[66:81], v[182:185], v[98:101], v[66:81]
	v_mfma_f32_32x32x16_bf16 v[82:97], v[186:189], v[102:105], v[82:97]
	v_mfma_f32_32x32x16_bf16 v[66:81], v[178:181], v[102:105], v[66:81]
	v_max3_f32 v230, v18, v19, v20
	v_max3_f32 v231, v21, v22, v23
	v_max3_f32 v232, v24, v25, v26
	v_max3_f32 v233, v27, v28, v29
	v_max3_f32 v230, v230, v30, v31
	v_max3_f32 v231, v231, v32, v33
	v_max3_f32 v230, v230, v231, v232
	v_max_f32_e32 v230, v230, v233
	v_mul_f32_e32 v230, s98, v230
	v_mov_b32_e32 v231, v230
	s_nop 1
	v_permlane32_swap_b32_e32 v230, v231
	v_max3_f32 v221, v225, v230, v231
	v_sub_f32_e32 v232, v225, v221
	v_exp_f32_e32 v228, v232
	v_fma_f32 v18, v18, s98, -v221
	v_fma_f32 v19, v19, s98, -v221
	v_fma_f32 v20, v20, s98, -v221
	v_fma_f32 v21, v21, s98, -v221
	v_fma_f32 v22, v22, s98, -v221
	v_fma_f32 v23, v23, s98, -v221
	v_fma_f32 v24, v24, s98, -v221
	v_fma_f32 v25, v25, s98, -v221
	v_fma_f32 v26, v26, s98, -v221
	v_fma_f32 v27, v27, s98, -v221
	v_fma_f32 v28, v28, s98, -v221
	v_fma_f32 v29, v29, s98, -v221
	v_fma_f32 v30, v30, s98, -v221
	v_fma_f32 v31, v31, s98, -v221
	v_fma_f32 v32, v32, s98, -v221
	v_fma_f32 v33, v33, s98, -v221
	v_exp_f32_e32 v18, v18
	v_exp_f32_e32 v19, v19
	v_exp_f32_e32 v20, v20
	v_exp_f32_e32 v21, v21
	v_exp_f32_e32 v22, v22
	v_exp_f32_e32 v23, v23
	v_exp_f32_e32 v24, v24
	v_exp_f32_e32 v25, v25
	v_exp_f32_e32 v26, v26
	v_exp_f32_e32 v27, v27
	v_exp_f32_e32 v28, v28
	v_exp_f32_e32 v29, v29
	v_exp_f32_e32 v30, v30
	v_exp_f32_e32 v31, v31
	v_exp_f32_e32 v32, v32
	v_exp_f32_e32 v33, v33
	v_cmp_lt_f32_e32 vcc, v225, v221
	v_mov_b32_e32 v225, v221
	v_cvt_pk_bf16_f32 v106, v18, v19
	v_cvt_pk_bf16_f32 v107, v20, v21
	v_cvt_pk_bf16_f32 v108, v22, v23
	v_cvt_pk_bf16_f32 v109, v24, v25
	v_cvt_pk_bf16_f32 v110, v26, v27
	v_cvt_pk_bf16_f32 v111, v28, v29
	v_cvt_pk_bf16_f32 v112, v30, v31
	v_cvt_pk_bf16_f32 v113, v32, v33
	v_add_f32_e32 v230, v18, v19
	v_add_f32_e32 v231, v20, v21
	v_add_f32_e32 v232, v22, v23
	v_add_f32_e32 v233, v24, v25
	v_add_f32_e32 v230, v230, v26
	v_add_f32_e32 v231, v231, v27
	v_add_f32_e32 v232, v232, v28
	v_add_f32_e32 v233, v233, v29
	v_add_f32_e32 v230, v230, v30
	v_add_f32_e32 v231, v231, v31
	v_add_f32_e32 v232, v232, v32
	v_add_f32_e32 v233, v233, v33
	v_add_f32_e32 v230, v230, v231
	v_add_f32_e32 v232, v232, v233
	v_add_f32_e32 v230, v230, v232
	v_fmac_f32_e32 v230, v219, v228
	v_mov_b32_e32 v219, v230
	s_cbranch_vccz .Lfx_nr1
	v_pk_mul_f32 v[50:51], v[50:51], v[228:229] op_sel_hi:[1,0]
	v_pk_mul_f32 v[52:53], v[52:53], v[228:229] op_sel_hi:[1,0]
	v_pk_mul_f32 v[54:55], v[54:55], v[228:229] op_sel_hi:[1,0]
	v_pk_mul_f32 v[56:57], v[56:57], v[228:229] op_sel_hi:[1,0]
	v_pk_mul_f32 v[58:59], v[58:59], v[228:229] op_sel_hi:[1,0]
	v_pk_mul_f32 v[60:61], v[60:61], v[228:229] op_sel_hi:[1,0]
	v_pk_mul_f32 v[62:63], v[62:63], v[228:229] op_sel_hi:[1,0]
	v_pk_mul_f32 v[64:65], v[64:65], v[228:229] op_sel_hi:[1,0]
	v_pk_mul_f32 v[34:35], v[34:35], v[228:229] op_sel_hi:[1,0]
	v_pk_mul_f32 v[36:37], v[36:37], v[228:229] op_sel_hi:[1,0]
	v_pk_mul_f32 v[38:39], v[38:39], v[228:229] op_sel_hi:[1,0]
	v_pk_mul_f32 v[40:41], v[40:41], v[228:229] op_sel_hi:[1,0]
	v_pk_mul_f32 v[42:43], v[42:43], v[228:229] op_sel_hi:[1,0]
	v_pk_mul_f32 v[44:45], v[44:45], v[228:229] op_sel_hi:[1,0]
	v_pk_mul_f32 v[46:47], v[46:47], v[228:229] op_sel_hi:[1,0]
	v_pk_mul_f32 v[48:49], v[48:49], v[228:229] op_sel_hi:[1,0]
	s_nop 1
.Lfx_nr1:
	v_mfma_f32_32x32x16_bf16 v[50:65], v[190:193], v[106:109], v[50:65]
	v_mfma_f32_32x32x16_bf16 v[34:49], v[182:185], v[106:109], v[34:49]
	v_mfma_f32_32x32x16_bf16 v[50:65], v[186:189], v[110:113], v[50:65]
	v_mfma_f32_32x32x16_bf16 v[34:49], v[178:181], v[110:113], v[34:49]
	s_and_b64 vcc, exec, s[4:5]
	s_cbranch_vccnz .Lfx_exit
	s_add_i32 s14, s14, -1
	v_add_u32_e32 v0, 0xffffff7c, v0
	v_lshl_add_u64 v[216:217], v[216:217], 0, s[84:85]
	s_cmp_le_i32 s14, s73
	s_cselect_b64 s[4:5], -1, 0
	s_add_i32 s100, s14, -1
	s_cmp_le_i32 s14, s73
	s_cselect_b32 s76, s14, s100
	s_lshl_b64 s[16:17], s[76:77], 12
	ds_read2_b32 v[114:115], v0 offset1:1
	ds_read2_b32 v[116:117], v0 offset0:2 offset1:3
	ds_read2_b32 v[118:119], v0 offset0:8 offset1:9
	ds_read2_b32 v[120:121], v0 offset0:10 offset1:11
	ds_read2_b32 v[122:123], v0 offset0:16 offset1:17
	ds_read2_b32 v[124:125], v0 offset0:18 offset1:19
	ds_read2_b32 v[126:127], v0 offset0:24 offset1:25
	ds_read2_b32 v[128:129], v0 offset0:26 offset1:27
	s_waitcnt vmcnt(0)
	v_mov_b32_e32 v206, v174
	v_mov_b32_e32 v207, v175
	v_mov_b32_e32 v208, v176
	v_mov_b32_e32 v209, v177
	v_mov_b32_e32 v202, v170
	v_mov_b32_e32 v203, v171
	v_mov_b32_e32 v204, v172
	v_mov_b32_e32 v205, v173
	v_mov_b32_e32 v198, v166
	v_mov_b32_e32 v199, v167
	v_mov_b32_e32 v200, v168
	v_mov_b32_e32 v201, v169
	v_mov_b32_e32 v194, v162
	v_mov_b32_e32 v195, v163
	v_mov_b32_e32 v196, v164
	v_mov_b32_e32 v197, v165
	global_load_dwordx4 v[190:193], v[216:217], off offset:-2048
	global_load_dwordx4 v[186:189], v[216:217], off offset:-1024
	global_load_dwordx4 v[182:185], v[216:217], off
	global_load_dwordx4 v[178:181], v[216:217], off offset:1024
	v_lshl_add_u64 v[234:235], v[214:215], 0, s[16:17]
	global_load_dwordx4 v[174:177], v[234:235], off
	global_load_dwordx4 v[170:173], v[234:235], off offset:1024
	global_load_dwordx4 v[166:169], v[234:235], off offset:2048
	global_load_dwordx4 v[162:165], v[234:235], off offset:3072
	s_branch .Lfx_iter
.Lfx_exit:
	s_waitcnt vmcnt(0)
	v_mov_b32_e32 v222, v218
	v_mov_b32_e32 v223, v219
	v_mov_b32_e32 v250, v224
	v_mov_b32_e32 v251, v225
	v_mov_b64_e32 v[2:3], v[82:83]
	v_mov_b64_e32 v[4:5], v[84:85]
	v_mov_b64_e32 v[6:7], v[86:87]
	v_mov_b64_e32 v[8:9], v[88:89]
	v_mov_b64_e32 v[10:11], v[90:91]
	v_mov_b64_e32 v[12:13], v[92:93]
	v_mov_b64_e32 v[14:15], v[94:95]
	v_mov_b64_e32 v[16:17], v[96:97]
	v_mov_b64_e32 v[18:19], v[66:67]
	v_mov_b64_e32 v[20:21], v[68:69]
	v_mov_b64_e32 v[22:23], v[70:71]
	v_mov_b64_e32 v[24:25], v[72:73]
	v_mov_b64_e32 v[26:27], v[74:75]
	v_mov_b64_e32 v[28:29], v[76:77]
	v_mov_b64_e32 v[30:31], v[78:79]
	v_mov_b64_e32 v[32:33], v[80:81]
	v_mov_b64_e32 v[98:99], v[50:51]
	v_mov_b64_e32 v[100:101], v[52:53]
	v_mov_b64_e32 v[102:103], v[54:55]
	v_mov_b64_e32 v[104:105], v[56:57]
	v_mov_b64_e32 v[106:107], v[58:59]
	v_mov_b64_e32 v[108:109], v[60:61]
	v_mov_b64_e32 v[110:111], v[62:63]
	v_mov_b64_e32 v[112:113], v[64:65]
	v_mov_b64_e32 v[114:115], v[34:35]
	v_mov_b64_e32 v[116:117], v[36:37]
	v_mov_b64_e32 v[118:119], v[38:39]
	v_mov_b64_e32 v[120:121], v[40:41]
	v_mov_b64_e32 v[122:123], v[42:43]
	v_mov_b64_e32 v[124:125], v[44:45]
	v_mov_b64_e32 v[126:127], v[46:47]
	v_mov_b64_e32 v[128:129], v[48:49]
	s_add_i32 s14, s14, -1
	s_branch .LBB0_442
